# adds: O4 and E3 queue orders interleave the two item kinds
# speedup vs baseline: 1.0313x; 1.0014x over previous
.LBB0_504:
	s_or_b64 exec, exec, s[14:15]
	v_mov_b32_e32 v0, s69
	s_waitcnt vmcnt(0) lgkmcnt(0)
	s_barrier
	ds_read_b32 v0, v0
	s_movk_i32 s4, 0x23f
	s_mov_b64 s[14:15], -1
	s_waitcnt lgkmcnt(0)
	s_barrier
	v_cmp_lt_i32_e32 vcc, s4, v0
	v_readfirstlane_b32 s6, v0
	s_cbranch_vccnz .LBB0_499
	s_cmpk_lt_u32 s6, 0x180
	s_cbranch_scc0 .Lo4_noremap
	s_lshr_b32 s96, s6, 1
	s_bitcmp1_b32 s6, 0
	s_cselect_b32 s97, 0xc0, 0
	s_add_i32 s6, s96, s97
.Lo4_noremap:
	s_cmpk_gt_i32 s6, 0xbf
	s_cbranch_scc0 .LBB0_524
	s_add_i32 s7, s6, 0xffffff40
	s_cmpk_lt_u32 s7, 0x80
	s_cselect_b64 s[42:43], -1, 0
	s_lshl_b32 s10, s7, 6
	v_mov_b32_e32 v2, v202
	v_mov_b32_e32 v0, v202
	s_cmpk_gt_u32 s7, 0x7f
	s_cbranch_scc0 .LBB0_508
	s_lshl_b32 s4, s7, 4
	s_and_b32 s4, s4, 0x1f00
	s_add_i32 s40, s4, 0xfffff800
	s_and_b32 s4, s10, 0xc0
	s_lshr_b32 s18, s7, 2
	s_or_b32 s38, s40, s4
	s_mov_b64 s[14:15], 0

.LBB0_574:
	s_or_b64 exec, exec, s[0:1]
	v_mov_b32_e32 v0, s69
	s_waitcnt vmcnt(0) lgkmcnt(0)
	s_barrier
	ds_read_b32 v0, v0
	s_movk_i32 s0, 0x2ff
	s_waitcnt lgkmcnt(0)
	s_barrier
	v_cmp_lt_i32_e32 vcc, s0, v0
	v_readfirstlane_b32 s3, v0
	s_mov_b64 s[0:1], -1
	s_cbranch_vccnz .LBB0_569
	s_cmpk_lt_u32 s3, 0x100
	s_cbranch_scc1 .Le3_noremap
	s_add_i32 s97, s3, 0xffffff00
	s_lshr_b32 s97, s97, 1
	s_movk_i32 s96, 0x100
	s_bitcmp1_b32 s3, 0
	s_cselect_b32 s96, 0x200, s96
	s_add_i32 s3, s96, s97
.Le3_noremap:
	s_cmpk_lt_i32 s3, 0x80
	s_cselect_b64 s[0:1], -1, 0
	s_and_b64 vcc, exec, s[0:1]
	s_cbranch_vccnz .LBB0_581
	s_and_b32 s0, s3, 0x7fffff00
	s_cmpk_lg_i32 s0, 0x100
	s_mov_b64 s[0:1], -1
	s_cbranch_scc0 .LBB0_594
	s_cmpk_lt_u32 s3, 0x100
	s_movk_i32 s0, 0xfe80
	s_cselect_b32 s1, 0xffffff80, s0
	s_add_i32 s1, s1, s3
	s_lshl_b32 s6, s1, 6
	v_mov_b32_e32 v0, v202
	v_mov_b32_e32 v2, v202
	s_cmpk_gt_i32 s1, 0x7f
	s_mov_b64 s[14:15], -1
	s_cbranch_scc0 .LBB0_579
	s_lshl_b32 s0, s1, 4
	s_and_b32 s0, s0, 0x7fffff00
	s_add_i32 s24, s0, 0xfffff800
	s_and_b32 s0, s6, 0xc0
	s_lshr_b32 s11, s1, 2
	s_or_b32 s0, s24, s0
	s_mov_b64 s[14:15], 0
